# lru_item: conversion (and wait) of the 19 conv-tap loads moved behind the issue of the main load batch, one far round trip instead of two
# speedup vs baseline: 1.0031x; 1.0025x over previous
; __device__ __forceinline__ bf16_t f2bf(float f) { return (bf16_t)(pk2(f, 0.f) & 0xffffu); }
; __device__ __forceinline__ float bf2f(unsigned b) { return __uint_as_float(b << 16); }
; __device__ __forceinline__ void lru_item(const Params& p, int l, int item, LAS unsigned char* lds) {
;     ...
;     unsigned xr[19];
; #pragma unroll
;     for (int i = 0; i < 19; ++i) { const int t = t0 - 3 + i; xr[i] = (t >= 0) ? (unsigned)p.z[(Tb + (t >= 0 ? t : 0)) * ZLD + 2304 + ch] : 0u; }
;     bf16x8 wa0[4], wa1[4], wx0[4], wx1[4];
;     { const bf16_t* wap = p.waT + (((size_t)l * 4 + h) * 64 + fr) * 64 + fq * 8; const bf16_t* wxp = p.wxT + (((size_t)l * 4 + h) * 64 + fr) * 64 + fq * 8;
; #pragma unroll
;       for (int jt = 0; jt < 4; ++jt) { wa0[jt] = *(const bf16x8*)(wap + jt * 1024); wa1[jt] = *(const bf16x8*)(wap + jt * 1024 + 32); wx0[jt] = *(const bf16x8*)(wxp + jt * 1024); wx1[jt] = *(const bf16x8*)(wxp + jt * 1024 + 32); } }
;     { const float cb = p.conv_b[l * 256 + ch], cw0 = p.conv_w[(l * 4 + 0) * 256 + ch], cw1 = p.conv_w[(l * 4 + 1) * 256 + ch], cw2 = p.conv_w[(l * 4 + 2) * 256 + ch], cw3 = p.conv_w[(l * 4 + 3) * 256 + ch];
; #pragma unroll
;       for (int i = 0; i < 16; ++i) { const float xc = cb + bf2f(xr[i]) * cw0 + bf2f(xr[i + 1]) * cw1 + bf2f(xr[i + 2]) * cw2 + bf2f(xr[i + 3]) * cw3; xa[i * 72 + lane] = f2bf(xc); xf[i * 66 + lane] = xc; } }
;     ...
;           const int cj = l * 256 + h * 64 + jt * 16 + fr; const float bav = p.ba[cj], bxv = p.bx[cj], sp = p.spl[cj];
.LBB0_393:
	s_or_b64 exec, exec, s[74:75]
	s_movk_i32 s4, 0x2a00
	v_and_b32_e32 v91, 15, v1
	s_or_b32 s98, s16, s40
	v_or_b32_e32 v148, s98, v91
	v_ashrrev_i32_e32 v149, 31, v148
	v_lshlrev_b64 v[148:149], 2, v[148:149]
	v_lshl_add_u64 v[150:151], s[30:31], 0, v[148:149]
	v_lshl_add_u64 v[152:153], s[6:7], 0, v[148:149]
	v_lshl_add_u64 v[154:155], s[34:35], 0, v[148:149]
	global_load_dword v156, v[150:151], off
	global_load_dword v157, v[152:153], off
	global_load_dword v158, v[154:155], off
	global_load_dword v159, v[150:151], off offset:64
	global_load_dword v160, v[152:153], off offset:64
	global_load_dword v161, v[154:155], off offset:64
	global_load_dword v162, v[150:151], off offset:128
	global_load_dword v163, v[152:153], off offset:128
	global_load_dword v164, v[154:155], off offset:128
	global_load_dword v165, v[150:151], off offset:192
	global_load_dword v166, v[152:153], off offset:192
	global_load_dword v167, v[154:155], off offset:192
	v_mul_lo_u32 v4, v0, s4
	s_or_b32 s4, s12, s16
	v_add_u32_e32 v79, 0, v4
	v_or_b32_e32 v4, s4, v91
	v_mov_b32_e32 v5, s13
	v_lshlrev_b64 v[4:5], 7, v[4:5]
	v_lshl_add_u64 v[6:7], s[70:71], 0, v[4:5]
	v_and_b32_e32 v20, 48, v3
	v_mov_b32_e32 v21, v2
	v_lshl_add_u64 v[6:7], v[6:7], 0, v[20:21]
	v_lshl_add_u64 v[4:5], s[36:37], 0, v[4:5]
	v_add_co_u32_e32 v8, vcc, s80, v6
	v_lshl_add_u64 v[4:5], v[4:5], 0, v[20:21]
	s_nop 0
	v_addc_co_u32_e32 v9, vcc, 0, v7, vcc
	v_or_b32_e32 v100, s40, v78
	v_mov_b32_e32 v98, s17
	v_mov_b32_e32 v99, s22
	v_add_co_u32_e32 v16, vcc, s80, v4
	v_ashrrev_i32_e32 v101, 31, v100
	s_nop 0
	v_addc_co_u32_e32 v17, vcc, 0, v5, vcc
	v_lshl_add_u64 v[98:99], v[100:101], 2, v[98:99]
	global_load_dwordx4 v[60:63], v[6:7], off
	global_load_dwordx4 v[64:67], v[6:7], off offset:64
	global_load_dwordx4 v[68:71], v[4:5], off
	global_load_dwordx4 v[72:75], v[4:5], off offset:64
	global_load_dwordx4 v[44:47], v[6:7], off offset:2048
	global_load_dwordx4 v[48:51], v[6:7], off offset:2112
	global_load_dwordx4 v[52:55], v[4:5], off offset:2048
	global_load_dwordx4 v[56:59], v[4:5], off offset:2112
	global_load_dwordx4 v[28:31], v[8:9], off
	global_load_dwordx4 v[32:35], v[8:9], off offset:64
	global_load_dwordx4 v[36:39], v[16:17], off
	global_load_dwordx4 v[40:43], v[16:17], off offset:64
	s_nop 0
	global_load_dwordx4 v[4:7], v[8:9], off offset:2048
	s_nop 0
	global_load_dwordx4 v[8:11], v[8:9], off offset:2112
	s_nop 0
	global_load_dwordx4 v[12:15], v[16:17], off offset:2048
	s_nop 0
	global_load_dwordx4 v[16:19], v[16:17], off offset:2112
	v_mov_b32_e32 v96, s33
	global_load_dword v21, v[98:99], off
	v_or_b32_e32 v98, s87, v78
	v_mov_b32_e32 v97, s44
	v_ashrrev_i32_e32 v99, 31, v98
	v_lshl_add_u64 v[96:97], v[98:99], 2, v[96:97]
	global_load_dword v98, v[96:97], off
	global_load_dword v99, v[96:97], off offset:1024
	global_load_dword v100, v[96:97], off offset:2048
	s_nop 0
	global_load_dword v96, v[96:97], off offset:3072
	v_lshlrev_b32_e32 v78, 1, v3
	v_add_u32_e32 v97, v79, v78
	v_add_u32_e32 v80, v97, v78
	s_or_b32 s4, s16, s40
	s_mov_b32 s16, 0xf800000
	v_lshrrev_b32_e32 v92, 4, v3
	v_lshl_add_u32 v1, v1, 3, 0
	v_add_u32_e32 v1, 0x15000, v1
	s_waitcnt vmcnt(3)
	v_lshlrev_b32_e32 v88, 16, v88
	v_lshlrev_b32_e32 v87, 16, v87
	v_lshlrev_b32_e32 v85, 16, v85
	v_lshlrev_b32_e32 v83, 16, v83
	v_lshlrev_b32_e32 v26, 16, v26
	v_lshlrev_b32_e32 v22, 16, v22
	v_lshlrev_b32_e32 v24, 16, v24
	v_lshlrev_b32_e32 v23, 16, v23
	v_lshlrev_b32_e32 v27, 16, v27
	v_lshlrev_b32_e32 v25, 16, v25
	v_lshlrev_b32_e32 v82, 16, v82
	v_lshlrev_b32_e32 v81, 16, v81
	v_lshlrev_b32_e32 v86, 16, v86
	v_lshlrev_b32_e32 v84, 16, v84
	v_lshlrev_b32_e32 v90, 16, v90
	v_lshlrev_b32_e32 v89, 16, v89
	v_lshlrev_b32_e32 v94, 16, v94
	v_lshlrev_b32_e32 v93, 16, v93
	v_lshlrev_b32_e32 v95, 16, v95
	v_cmp_lt_i32_e32 vcc, 2, v76
	s_nop 1
	v_cndmask_b32_e32 v88, 0, v88, vcc
	v_cmp_lt_i32_e32 vcc, 1, v76
	s_nop 1
	v_cndmask_b32_e32 v87, 0, v87, vcc
	v_cmp_lt_i32_e32 vcc, 0, v76
	s_nop 1
	v_cndmask_b32_e32 v85, 0, v85, vcc
	v_fma_f32 v88, v88, v98, v21
	s_waitcnt vmcnt(2)
	v_fmac_f32_e32 v88, v87, v99
	v_fma_f32 v87, v87, v98, v21
	s_waitcnt vmcnt(1)
	v_fmac_f32_e32 v88, v85, v100
	v_fmac_f32_e32 v87, v85, v99
	s_waitcnt vmcnt(0)
	v_fmac_f32_e32 v88, v83, v96
	v_cvt_pk_bf16_f32 v101, v88, v2
	v_fmac_f32_e32 v87, v83, v100
	v_fma_f32 v85, v85, v98, v21
	ds_write_b16 v97, v101
	v_fmac_f32_e32 v87, v26, v96
	v_cvt_pk_bf16_f32 v101, v87, v2
	v_fmac_f32_e32 v85, v83, v99
	v_fma_f32 v83, v83, v98, v21
	ds_write_b16 v97, v101 offset:144
	v_add_u32_e32 v101, 0x800, v80
	v_fmac_f32_e32 v85, v26, v100
	v_fmac_f32_e32 v83, v26, v99
	ds_write2_b32 v101, v88, v87 offset0:64 offset1:130
	v_fmac_f32_e32 v85, v22, v96
	v_cvt_pk_bf16_f32 v87, v85, v2
	v_fmac_f32_e32 v83, v22, v100
	v_fma_f32 v26, v26, v98, v21
	ds_write_b16 v97, v87 offset:288
	v_fmac_f32_e32 v83, v24, v96
	v_cvt_pk_bf16_f32 v87, v83, v2
	v_fmac_f32_e32 v26, v22, v99
	v_fma_f32 v22, v22, v98, v21
	ds_write_b16 v97, v87 offset:432
	v_add_u32_e32 v87, 0xa00, v80
	v_fmac_f32_e32 v26, v24, v100
	v_fmac_f32_e32 v22, v24, v99
	ds_write2_b32 v87, v85, v83 offset0:68 offset1:134
	v_fmac_f32_e32 v26, v23, v96
	v_cvt_pk_bf16_f32 v83, v26, v2
	v_fmac_f32_e32 v22, v23, v100
	ds_write_b16 v97, v83 offset:576
	v_fmac_f32_e32 v22, v27, v96
	v_cvt_pk_bf16_f32 v83, v22, v2
	ds_write_b16 v97, v83 offset:720
	v_add_u32_e32 v83, 0xc00, v80
	ds_write2_b32 v83, v26, v22 offset0:72 offset1:138
	v_fma_f32 v22, v24, v98, v21
	v_fmac_f32_e32 v22, v23, v99
	v_fma_f32 v23, v23, v98, v21
	v_fmac_f32_e32 v22, v27, v100
	v_fmac_f32_e32 v23, v27, v99
	v_fmac_f32_e32 v22, v25, v96
	v_cvt_pk_bf16_f32 v24, v22, v2
; #define LAS __attribute__((address_space(3)))
; __device__ __forceinline__ bf16_t f2bf(float f) { return (bf16_t)(pk2(f, 0.f) & 0xffffu); }
; __device__ __forceinline__ float bf2f(unsigned b) { return __uint_as_float(b << 16); }
; __device__ __forceinline__ float fexp(float x) { return __builtin_amdgcn_exp2f(x * LOG2E); }
; __device__ __forceinline__ float sigm(float x) { return frcp(1.f + fexp(-x)); }
; __device__ __forceinline__ f32x4 mfma16(bf16x8 a, bf16x8 b, f32x4 c) { return __builtin_amdgcn_mfma_f32_16x16x32_bf16(a, b, c, 0, 0, 0); }
; __device__ __forceinline__ void lds_barrier() { asm volatile("s_waitcnt lgkmcnt(0)" ::: "memory"); __builtin_amdgcn_s_barrier(); asm volatile("" ::: "memory"); }
; __device__ __forceinline__ void lru_item(const Params& p, int l, int item, LAS unsigned char* lds) {
;     ...
;       for (int i = 0; i < 16; ++i) { const float xc = cb + bf2f(xr[i]) * cw0 + bf2f(xr[i + 1]) * cw1 + bf2f(xr[i + 2]) * cw2 + bf2f(xr[i + 3]) * cw3; xa[i * 72 + lane] = f2bf(xc); xf[i * 66 + lane] = xc; } }
;     lds_barrier();
;     { const bf16x8 a0 = *(const LAS bf16x8*)(xa + fr * 72 + fq * 8), a1 = *(const LAS bf16x8*)(xa + fr * 72 + 32 + fq * 8);
; #pragma unroll
;       for (int jt = 0; jt < 4; ++jt) {
;           f32x4 pa = mfma16(a0, wa0[jt], ZERO4); pa = mfma16(a1, wa1[jt], pa);
;           f32x4 px = mfma16(a0, wx0[jt], ZERO4); px = mfma16(a1, wx1[jt], px);
;           const int cj = l * 256 + h * 64 + jt * 16 + fr; const float bav = p.ba[cj], bxv = p.bx[cj], sp = p.spl[cj];
; #pragma unroll
;           for (int jj = 0; jj < 4; ++jj) { const int t = fq * 4 + jj; const float r = sigm(pa[jj] + bav), ig = sigm(px[jj] + bxv); const float la = -8.f * r * sp;
;               const float a = fexp(la); float mult = sqrtf(fmaxf(1.f - fexp(2.f * la), 0.f)); if (t0 + t == 0) mult = 1.f;
;               const int li = t * 66 + jt * 16 + fr; const float xcv = xf[li]; sa[li] = a; xf[li] = mult * ig * xcv; }
	v_fmac_f32_e32 v23, v25, v100
	ds_write_b16 v97, v24 offset:864
	v_fmac_f32_e32 v23, v82, v96
	v_cvt_pk_bf16_f32 v24, v23, v2
	ds_write_b16 v97, v24 offset:1008
	v_add_u32_e32 v24, 0xe00, v80
	ds_write2_b32 v24, v22, v23 offset0:76 offset1:142
	v_fma_f32 v22, v27, v98, v21
	v_fmac_f32_e32 v22, v25, v99
	v_fmac_f32_e32 v22, v82, v100
	v_fmac_f32_e32 v22, v81, v96
	v_cvt_pk_bf16_f32 v23, v22, v2
	ds_write_b16 v97, v23 offset:1152
	v_fma_f32 v23, v25, v98, v21
	v_fmac_f32_e32 v23, v82, v99
	v_fmac_f32_e32 v23, v81, v100
	v_fmac_f32_e32 v23, v86, v96
	v_cvt_pk_bf16_f32 v24, v23, v2
	ds_write_b16 v97, v24 offset:1296
	v_add_u32_e32 v24, 0x1000, v80
	ds_write2_b32 v24, v22, v23 offset0:80 offset1:146
	v_fma_f32 v22, v82, v98, v21
	v_fmac_f32_e32 v22, v81, v99
	v_fmac_f32_e32 v22, v86, v100
	v_fmac_f32_e32 v22, v84, v96
	v_cvt_pk_bf16_f32 v23, v22, v2
	ds_write_b16 v97, v23 offset:1440
	v_fma_f32 v23, v81, v98, v21
	v_fmac_f32_e32 v23, v86, v99
	v_fmac_f32_e32 v23, v84, v100
	v_fmac_f32_e32 v23, v90, v96
	v_cvt_pk_bf16_f32 v24, v23, v2
	ds_write_b16 v97, v24 offset:1584
	v_add_u32_e32 v24, 0x1200, v80
	ds_write2_b32 v24, v22, v23 offset0:84 offset1:150
	v_fma_f32 v22, v86, v98, v21
	v_fmac_f32_e32 v22, v84, v99
	v_fmac_f32_e32 v22, v90, v100
	v_fmac_f32_e32 v22, v89, v96
	v_cvt_pk_bf16_f32 v23, v22, v2
	ds_write_b16 v97, v23 offset:1728
	v_fma_f32 v23, v84, v98, v21
	v_fmac_f32_e32 v23, v90, v99
	v_fmac_f32_e32 v23, v89, v100
	v_fmac_f32_e32 v23, v94, v96
	v_cvt_pk_bf16_f32 v24, v23, v2
	ds_write_b16 v97, v24 offset:1872
	v_add_u32_e32 v24, 0x1400, v80
	ds_write2_b32 v24, v22, v23 offset0:88 offset1:154
	v_fma_f32 v22, v90, v98, v21
	v_fmac_f32_e32 v22, v89, v99
	v_fmac_f32_e32 v21, v89, v98
	v_fmac_f32_e32 v22, v94, v100
	v_fmac_f32_e32 v21, v94, v99
	v_fmac_f32_e32 v22, v93, v96
	v_cvt_pk_bf16_f32 v23, v22, v2
	v_fmac_f32_e32 v21, v93, v100
	ds_write_b16 v97, v23 offset:2016
	v_fmac_f32_e32 v21, v95, v96
	v_cvt_pk_bf16_f32 v23, v21, v2
	ds_write_b16 v97, v23 offset:2160
	v_add_u32_e32 v23, 0x1600, v80
	ds_write2_b32 v23, v22, v21 offset0:92 offset1:158
	v_mul_u32_u24_e32 v21, 0x90, v91
	s_waitcnt lgkmcnt(0)
	s_barrier
	v_add3_u32 v24, v79, v21, v20
	ds_read_b128 v[20:23], v24
	ds_read_b128 v[24:27], v24 offset:64
	s_waitcnt lgkmcnt(1)
	v_mfma_f32_16x16x32_bf16 v[60:63], v[20:23], v[60:63], 0
	v_or_b32_e32 v86, s4, v91
	v_ashrrev_i32_e32 v87, 31, v86
	s_waitcnt lgkmcnt(0)
	v_mfma_f32_16x16x32_bf16 v[82:85], v[24:27], v[64:67], v[60:63]
	v_mfma_f32_16x16x32_bf16 v[60:63], v[20:23], v[68:71], 0
	v_mfma_f32_16x16x32_bf16 v[70:73], v[24:27], v[72:75], v[60:63]
	v_mfma_f32_16x16x32_bf16 v[44:47], v[20:23], v[44:47], 0
	s_nop 5
	v_lshlrev_b64 v[60:61], 2, v[86:87]
	v_lshl_add_u64 v[64:65], s[30:31], 0, v[60:61]
	v_lshl_add_u64 v[62:63], s[6:7], 0, v[60:61]
	v_lshl_add_u64 v[60:61], s[34:35], 0, v[60:61]
	v_mfma_f32_16x16x32_bf16 v[48:51], v[24:27], v[48:51], v[44:47]
	s_waitcnt vmcnt(0)
	v_mov_b32_e32 v81, v156
	v_mov_b32_e32 v86, v157
	v_mov_b32_e32 v87, v158
	v_add_f32_e32 v66, v82, v81
	v_mul_f32_e32 v66, 0xbfb8aa3b, v66
	v_exp_f32_e32 v66, v66
	s_waitcnt vmcnt(1)
	v_add_f32_e32 v67, v70, v86
	v_mul_f32_e32 v67, 0xbfb8aa3b, v67
	v_exp_f32_e32 v67, v67
	v_add_f32_e32 v66, 1.0, v66
	v_rcp_f32_e32 v66, v66
	v_mfma_f32_16x16x32_bf16 v[44:47], v[20:23], v[52:55], 0
	v_add_f32_e32 v67, 1.0, v67
	v_rcp_f32_e32 v68, v67
	v_mul_f32_e32 v66, 0xc1000000, v66
	s_waitcnt vmcnt(0)
	v_mul_f32_e32 v66, v87, v66
	v_mul_f32_e32 v67, 0x3fb8aa3b, v66
	v_add_f32_e32 v66, v66, v66
	v_mul_f32_e32 v66, 0x3fb8aa3b, v66
	v_exp_f32_e32 v66, v66
	v_exp_f32_e32 v69, v67
	v_mfma_f32_16x16x32_bf16 v[44:47], v[24:27], v[56:59], v[44:47]
	v_sub_f32_e32 v66, 1.0, v66
	v_max_f32_e32 v66, 0, v66
	v_cmp_gt_f32_e32 vcc, s16, v66
	v_mul_f32_e32 v67, 0x4f800000, v66
	v_mfma_f32_16x16x32_bf16 v[28:31], v[20:23], v[28:31], 0
	v_cndmask_b32_e32 v66, v66, v67, vcc
	v_sqrt_f32_e32 v67, v66
	v_mfma_f32_16x16x32_bf16 v[32:35], v[24:27], v[32:35], v[28:31]
	v_add_u32_e32 v70, -1, v67
	v_fma_f32 v74, -v70, v67, v66
	v_cmp_ge_f32_e64 s[4:5], 0, v74
	v_add_u32_e32 v74, 1, v67
	v_mfma_f32_16x16x32_bf16 v[28:31], v[20:23], v[36:39], 0
	v_cndmask_b32_e64 v70, v67, v70, s[4:5]
	v_fma_f32 v67, -v74, v67, v66
	v_cmp_lt_f32_e64 s[4:5], 0, v67
	v_mfma_f32_16x16x32_bf16 v[28:31], v[24:27], v[40:43], v[28:31]
	s_nop 0
	v_cndmask_b32_e64 v67, v70, v74, s[4:5]
	v_mul_f32_e32 v70, 0x37800000, v67
	v_cndmask_b32_e32 v67, v67, v70, vcc
	v_cmp_class_f32_e32 vcc, v66, v205
	s_movk_i32 s4, 0x108
	v_mfma_f32_16x16x32_bf16 v[4:7], v[20:23], v[4:7], 0
	v_cndmask_b32_e32 v66, v67, v66, vcc
	v_or_b32_e32 v67, v76, v92
	v_cmp_eq_u32_e32 vcc, 0, v67
	v_mfma_f32_16x16x32_bf16 v[8:11], v[24:27], v[8:11], v[4:7]
	s_nop 0
	v_cndmask_b32_e64 v70, v66, 1.0, vcc
	v_mad_u32_u24 v66, v92, s4, v91
	v_lshl_add_u32 v74, v66, 2, v79
	v_add_u32_e32 v75, 0x800, v74
	ds_read2_b32 v[66:67], v75 offset0:64 offset1:80
	v_mul_f32_e32 v68, v68, v70
	ds_write_b32 v74, v69 offset:6528
	v_mfma_f32_16x16x32_bf16 v[4:7], v[20:23], v[12:15], 0
	s_waitcnt lgkmcnt(1)
; __device__ __forceinline__ float fexp(float x) { return __builtin_amdgcn_exp2f(x * LOG2E); }
; __device__ __forceinline__ float sigm(float x) { return frcp(1.f + fexp(-x)); }
; __device__ __forceinline__ f32x4 mfma16(bf16x8 a, bf16x8 b, f32x4 c) { return __builtin_amdgcn_mfma_f32_16x16x32_bf16(a, b, c, 0, 0, 0); }
; __device__ __forceinline__ void lru_item(const Params& p, int l, int item, LAS unsigned char* lds) {
;     ...
;       for (int jt = 0; jt < 4; ++jt) {
;           f32x4 pa = mfma16(a0, wa0[jt], ZERO4); pa = mfma16(a1, wa1[jt], pa);
;           f32x4 px = mfma16(a0, wx0[jt], ZERO4); px = mfma16(a1, wx1[jt], px);
;           const int cj = l * 256 + h * 64 + jt * 16 + fr; const float bav = p.ba[cj], bxv = p.bx[cj], sp = p.spl[cj];
; #pragma unroll
;           for (int jj = 0; jj < 4; ++jj) { const int t = fq * 4 + jj; const float r = sigm(pa[jj] + bav), ig = sigm(px[jj] + bxv); const float la = -8.f * r * sp;
;               const float a = fexp(la); float mult = sqrtf(fmaxf(1.f - fexp(2.f * la), 0.f)); if (t0 + t == 0) mult = 1.f;
;               const int li = t * 66 + jt * 16 + fr; const float xcv = xf[li]; sa[li] = a; xf[li] = mult * ig * xcv; }
	v_mul_f32_e32 v66, v66, v68
	ds_write_b32 v74, v66 offset:2304
	v_add_f32_e32 v66, v83, v81
	v_mul_f32_e32 v66, 0xbfb8aa3b, v66
	v_exp_f32_e32 v66, v66
	v_add_f32_e32 v68, v71, v86
	v_mul_f32_e32 v68, 0xbfb8aa3b, v68
	v_exp_f32_e32 v68, v68
	v_add_f32_e32 v66, 1.0, v66
	v_rcp_f32_e32 v66, v66
	v_mfma_f32_16x16x32_bf16 v[4:7], v[24:27], v[16:19], v[4:7]
	v_add_f32_e32 v68, 1.0, v68
	v_rcp_f32_e32 v70, v68
	v_mul_f32_e32 v66, 0xc1000000, v66
	v_mul_f32_e32 v66, v87, v66
	v_mul_f32_e32 v68, 0x3fb8aa3b, v66
	v_add_f32_e32 v66, v66, v66
	v_mul_f32_e32 v66, 0x3fb8aa3b, v66
	v_exp_f32_e32 v66, v66
	v_exp_f32_e32 v71, v68
	v_sub_f32_e32 v66, 1.0, v66
	v_max_f32_e32 v66, 0, v66
	v_cmp_gt_f32_e64 s[4:5], s16, v66
	v_mul_f32_e32 v68, 0x4f800000, v66
	s_nop 0
	v_cndmask_b32_e64 v66, v66, v68, s[4:5]
	v_sqrt_f32_e32 v68, v66
	s_nop 0
	v_add_u32_e32 v69, -1, v68
	v_fma_f32 v76, -v69, v68, v66
	v_cmp_ge_f32_e64 s[6:7], 0, v76
	v_add_u32_e32 v76, 1, v68
	s_nop 0
	v_cndmask_b32_e64 v69, v68, v69, s[6:7]
	v_fma_f32 v68, -v76, v68, v66
	v_cmp_lt_f32_e64 s[6:7], 0, v68
	s_nop 1
	v_cndmask_b32_e64 v68, v69, v76, s[6:7]
	v_mul_f32_e32 v69, 0x37800000, v68
	v_cndmask_b32_e64 v68, v68, v69, s[4:5]
	v_cmp_class_f32_e64 s[4:5], v66, v205
	s_nop 1
	v_cndmask_b32_e64 v66, v68, v66, s[4:5]
	ds_read2_b32 v[68:69], v75 offset0:130 offset1:146
	v_mul_f32_e32 v66, v70, v66
	ds_write_b32 v74, v71 offset:6792
	s_waitcnt lgkmcnt(1)
	v_mul_f32_e32 v66, v68, v66
	ds_write_b32 v74, v66 offset:2568
	v_add_f32_e32 v66, v84, v81
	v_mul_f32_e32 v66, 0xbfb8aa3b, v66
	v_exp_f32_e32 v66, v66
	v_add_f32_e32 v68, v72, v86
	v_mul_f32_e32 v68, 0xbfb8aa3b, v68
	v_exp_f32_e32 v68, v68
	v_add_f32_e32 v66, 1.0, v66
	v_rcp_f32_e32 v66, v66
	v_add_f32_e32 v68, 1.0, v68
	v_rcp_f32_e32 v68, v68
	v_mul_f32_e32 v66, 0xc1000000, v66
	v_mul_f32_e32 v66, v87, v66
	v_mul_f32_e32 v70, 0x3fb8aa3b, v66
	v_add_f32_e32 v66, v66, v66
	v_mul_f32_e32 v66, 0x3fb8aa3b, v66
	v_exp_f32_e32 v66, v66
	v_exp_f32_e32 v72, v70
	v_sub_f32_e32 v66, 1.0, v66
	v_max_f32_e32 v66, 0, v66
	v_cmp_gt_f32_e64 s[4:5], s16, v66
	v_mul_f32_e32 v70, 0x4f800000, v66
	s_nop 0
	v_cndmask_b32_e64 v66, v66, v70, s[4:5]
	v_sqrt_f32_e32 v70, v66
	s_nop 0
	v_add_u32_e32 v71, -1, v70
	v_fma_f32 v76, -v71, v70, v66
	v_cmp_ge_f32_e64 s[6:7], 0, v76
	v_add_u32_e32 v76, 1, v70
	s_nop 0
	v_cndmask_b32_e64 v71, v70, v71, s[6:7]
	v_fma_f32 v70, -v76, v70, v66
	v_cmp_lt_f32_e64 s[6:7], 0, v70
	s_nop 1
	v_cndmask_b32_e64 v70, v71, v76, s[6:7]
	v_mul_f32_e32 v71, 0x37800000, v70
	v_cndmask_b32_e64 v70, v70, v71, s[4:5]
	v_cmp_class_f32_e64 s[4:5], v66, v205
	s_nop 1
	v_cndmask_b32_e64 v66, v70, v66, s[4:5]
	ds_read2_b32 v[70:71], v75 offset0:196 offset1:212
	v_mul_f32_e32 v66, v68, v66
	v_add_f32_e32 v68, v73, v86
	v_mul_f32_e32 v68, 0xbfb8aa3b, v68
	v_exp_f32_e32 v68, v68
	s_waitcnt lgkmcnt(0)
	v_mul_f32_e32 v66, v70, v66
	ds_write_b32 v74, v66 offset:2832
	v_add_f32_e32 v66, v85, v81
	v_mul_f32_e32 v66, 0xbfb8aa3b, v66
	v_exp_f32_e32 v66, v66
	v_add_f32_e32 v68, 1.0, v68
	v_rcp_f32_e32 v70, v68
	ds_write_b32 v74, v72 offset:7056
	v_add_f32_e32 v66, 1.0, v66
	v_rcp_f32_e32 v66, v66
	s_nop 0
	v_mul_f32_e32 v66, 0xc1000000, v66
	v_mul_f32_e32 v66, v87, v66
	v_mul_f32_e32 v68, 0x3fb8aa3b, v66
	v_add_f32_e32 v66, v66, v66
	v_mul_f32_e32 v66, 0x3fb8aa3b, v66
	v_exp_f32_e32 v66, v66
	v_exp_f32_e32 v68, v68
	v_sub_f32_e32 v66, 1.0, v66
	v_max_f32_e32 v66, 0, v66
	v_cmp_gt_f32_e64 s[4:5], s16, v66
	v_mul_f32_e32 v72, 0x4f800000, v66
	s_nop 0
	v_cndmask_b32_e64 v66, v66, v72, s[4:5]
	v_sqrt_f32_e32 v72, v66
	s_nop 0
	v_add_u32_e32 v73, -1, v72
	v_fma_f32 v76, -v73, v72, v66
	v_cmp_ge_f32_e64 s[6:7], 0, v76
	v_add_u32_e32 v76, 1, v72
	s_nop 0
	v_cndmask_b32_e64 v73, v72, v73, s[6:7]
	v_fma_f32 v72, -v76, v72, v66
	v_cmp_lt_f32_e64 s[6:7], 0, v72
	s_nop 1
	v_cndmask_b32_e64 v72, v73, v76, s[6:7]
	v_mul_f32_e32 v73, 0x37800000, v72
	v_cndmask_b32_e64 v72, v72, v73, s[4:5]
	v_cmp_class_f32_e64 s[4:5], v66, v205
	s_nop 1
	v_cndmask_b32_e64 v76, v72, v66, s[4:5]
	v_add_u32_e32 v66, 0xc00, v74
	ds_read2_b32 v[72:73], v66 offset0:6 offset1:22
	v_mov_b32_e32 v52, v159
	v_mov_b32_e32 v53, v160
	v_mov_b32_e32 v54, v161
	v_mul_f32_e32 v70, v70, v76
	s_waitcnt lgkmcnt(0)
	v_mul_f32_e32 v70, v72, v70
	s_waitcnt vmcnt(2)
	v_add_f32_e32 v48, v48, v52
	v_mul_f32_e32 v48, 0xbfb8aa3b, v48
	v_exp_f32_e32 v48, v48
	s_waitcnt vmcnt(1)
	v_add_f32_e32 v44, v44, v53
	v_mul_f32_e32 v44, 0xbfb8aa3b, v44
	v_exp_f32_e32 v44, v44
	v_add_f32_e32 v48, 1.0, v48
	v_rcp_f32_e32 v48, v48
	v_add_f32_e32 v45, v45, v53
	v_add_f32_e32 v44, 1.0, v44
	v_rcp_f32_e32 v44, v44
	v_mul_f32_e32 v48, 0xc1000000, v48
	s_waitcnt vmcnt(0)
; __device__ __forceinline__ float fexp(float x) { return __builtin_amdgcn_exp2f(x * LOG2E); }
; __device__ __forceinline__ float sigm(float x) { return frcp(1.f + fexp(-x)); }
; __device__ __forceinline__ f32x4 mfma16(bf16x8 a, bf16x8 b, f32x4 c) { return __builtin_amdgcn_mfma_f32_16x16x32_bf16(a, b, c, 0, 0, 0); }
; __device__ __forceinline__ void lru_item(const Params& p, int l, int item, LAS unsigned char* lds) {
;     ...
;       for (int jt = 0; jt < 4; ++jt) {
;           f32x4 pa = mfma16(a0, wa0[jt], ZERO4); pa = mfma16(a1, wa1[jt], pa);
;           f32x4 px = mfma16(a0, wx0[jt], ZERO4); px = mfma16(a1, wx1[jt], px);
;           const int cj = l * 256 + h * 64 + jt * 16 + fr; const float bav = p.ba[cj], bxv = p.bx[cj], sp = p.spl[cj];
; #pragma unroll
;           for (int jj = 0; jj < 4; ++jj) { const int t = fq * 4 + jj; const float r = sigm(pa[jj] + bav), ig = sigm(px[jj] + bxv); const float la = -8.f * r * sp;
;               const float a = fexp(la); float mult = sqrtf(fmaxf(1.f - fexp(2.f * la), 0.f)); if (t0 + t == 0) mult = 1.f;
;               const int li = t * 66 + jt * 16 + fr; const float xcv = xf[li]; sa[li] = a; xf[li] = mult * ig * xcv; }
	v_mul_f32_e32 v48, v54, v48
	v_mul_f32_e32 v55, 0x3fb8aa3b, v48
	v_add_f32_e32 v48, v48, v48
	v_mul_f32_e32 v48, 0x3fb8aa3b, v48
	v_exp_f32_e32 v48, v48
	v_exp_f32_e32 v55, v55
	v_mul_f32_e32 v45, 0xbfb8aa3b, v45
	v_exp_f32_e32 v45, v45
	v_sub_f32_e32 v48, 1.0, v48
	v_max_f32_e32 v48, 0, v48
	v_cmp_gt_f32_e64 s[4:5], s16, v48
	v_mul_f32_e32 v56, 0x4f800000, v48
	ds_write_b32 v74, v55 offset:6592
	v_cndmask_b32_e64 v48, v48, v56, s[4:5]
	v_sqrt_f32_e32 v56, v48
	v_add_f32_e32 v45, 1.0, v45
	v_rcp_f32_e32 v45, v45
	v_add_u32_e32 v57, -1, v56
	v_fma_f32 v58, -v57, v56, v48
	v_cmp_ge_f32_e64 s[6:7], 0, v58
	v_add_u32_e32 v58, 1, v56
	s_nop 0
	v_cndmask_b32_e64 v57, v56, v57, s[6:7]
	v_fma_f32 v56, -v58, v56, v48
	v_cmp_lt_f32_e64 s[6:7], 0, v56
	s_nop 1
	v_cndmask_b32_e64 v56, v57, v58, s[6:7]
	v_mul_f32_e32 v57, 0x37800000, v56
	v_cndmask_b32_e64 v56, v56, v57, s[4:5]
	v_cmp_class_f32_e64 s[4:5], v48, v205
	s_nop 1
	v_cndmask_b32_e64 v48, v56, v48, s[4:5]
	v_cndmask_b32_e64 v48, v48, 1.0, vcc
	v_mul_f32_e32 v44, v44, v48
	v_mul_f32_e32 v48, v67, v44
	v_add_f32_e32 v44, v49, v52
	v_mul_f32_e32 v44, 0xbfb8aa3b, v44
	v_exp_f32_e32 v44, v44
	s_nop 0
	v_add_f32_e32 v44, 1.0, v44
	v_rcp_f32_e32 v44, v44
	s_nop 0
	v_mul_f32_e32 v44, 0xc1000000, v44
	v_mul_f32_e32 v44, v54, v44
	v_mul_f32_e32 v49, 0x3fb8aa3b, v44
	v_add_f32_e32 v44, v44, v44
	v_mul_f32_e32 v44, 0x3fb8aa3b, v44
	v_exp_f32_e32 v44, v44
	v_exp_f32_e32 v49, v49
	v_sub_f32_e32 v44, 1.0, v44
	v_max_f32_e32 v44, 0, v44
	v_cmp_gt_f32_e64 s[4:5], s16, v44
	v_mul_f32_e32 v55, 0x4f800000, v44
	ds_write_b32 v74, v49 offset:6856
	v_cndmask_b32_e64 v44, v44, v55, s[4:5]
	v_sqrt_f32_e32 v55, v44
	s_nop 0
	v_add_u32_e32 v56, -1, v55
	v_fma_f32 v57, -v56, v55, v44
	v_cmp_ge_f32_e64 s[6:7], 0, v57
	v_add_u32_e32 v57, 1, v55
	s_nop 0
	v_cndmask_b32_e64 v56, v55, v56, s[6:7]
	v_fma_f32 v55, -v57, v55, v44
	v_cmp_lt_f32_e64 s[6:7], 0, v55
	s_nop 1
	v_cndmask_b32_e64 v55, v56, v57, s[6:7]
	v_mul_f32_e32 v56, 0x37800000, v55
	v_cndmask_b32_e64 v55, v55, v56, s[4:5]
	v_cmp_class_f32_e64 s[4:5], v44, v205
	s_nop 1
	v_cndmask_b32_e64 v44, v55, v44, s[4:5]
	v_mul_f32_e32 v44, v45, v44
	v_mul_f32_e32 v44, v69, v44
	ds_write_b32 v74, v44 offset:2632
	v_add_f32_e32 v44, v50, v52
	v_mul_f32_e32 v44, 0xbfb8aa3b, v44
	v_exp_f32_e32 v44, v44
	v_add_f32_e32 v45, v46, v53
	v_mul_f32_e32 v45, 0xbfb8aa3b, v45
	v_exp_f32_e32 v45, v45
	v_add_f32_e32 v44, 1.0, v44
	v_rcp_f32_e32 v44, v44
	v_add_f32_e32 v45, 1.0, v45
	v_rcp_f32_e32 v45, v45
	v_mul_f32_e32 v44, 0xc1000000, v44
	v_mul_f32_e32 v44, v54, v44
	v_mul_f32_e32 v46, 0x3fb8aa3b, v44
	v_add_f32_e32 v44, v44, v44
	v_mul_f32_e32 v44, 0x3fb8aa3b, v44
	v_exp_f32_e32 v44, v44
	v_exp_f32_e32 v46, v46
	v_sub_f32_e32 v44, 1.0, v44
	v_max_f32_e32 v44, 0, v44
	v_cmp_gt_f32_e64 s[4:5], s16, v44
	v_mul_f32_e32 v49, 0x4f800000, v44
	ds_write_b32 v74, v46 offset:7120
	v_cndmask_b32_e64 v44, v44, v49, s[4:5]
	v_sqrt_f32_e32 v49, v44
	s_nop 0
	v_add_u32_e32 v50, -1, v49
	v_fma_f32 v55, -v50, v49, v44
	v_cmp_ge_f32_e64 s[6:7], 0, v55
	v_add_u32_e32 v55, 1, v49
	s_nop 0
	v_cndmask_b32_e64 v50, v49, v50, s[6:7]
	v_fma_f32 v49, -v55, v49, v44
	v_cmp_lt_f32_e64 s[6:7], 0, v49
	s_nop 1
	v_cndmask_b32_e64 v49, v50, v55, s[6:7]
	v_mul_f32_e32 v50, 0x37800000, v49
	v_cndmask_b32_e64 v49, v49, v50, s[4:5]
	v_cmp_class_f32_e64 s[4:5], v44, v205
	s_nop 1
	v_cndmask_b32_e64 v44, v49, v44, s[4:5]
	v_mul_f32_e32 v44, v45, v44
	v_mul_f32_e32 v44, v71, v44
	ds_write_b32 v74, v44 offset:2896
	v_add_f32_e32 v44, v51, v52
	v_mul_f32_e32 v44, 0xbfb8aa3b, v44
	v_exp_f32_e32 v44, v44
	v_add_f32_e32 v45, v47, v53
	v_mul_f32_e32 v45, 0xbfb8aa3b, v45
	v_exp_f32_e32 v45, v45
	v_add_f32_e32 v44, 1.0, v44
	v_rcp_f32_e32 v44, v44
	v_add_f32_e32 v45, 1.0, v45
	v_rcp_f32_e32 v45, v45
	v_mul_f32_e32 v44, 0xc1000000, v44
	v_mul_f32_e32 v44, v54, v44
	v_mul_f32_e32 v46, 0x3fb8aa3b, v44
	v_add_f32_e32 v44, v44, v44
	v_mul_f32_e32 v44, 0x3fb8aa3b, v44
	v_exp_f32_e32 v44, v44
	v_exp_f32_e32 v46, v46
	v_sub_f32_e32 v44, 1.0, v44
	v_max_f32_e32 v44, 0, v44
	v_cmp_gt_f32_e64 s[4:5], s16, v44
	v_mul_f32_e32 v47, 0x4f800000, v44
	s_nop 0
	v_cndmask_b32_e64 v44, v44, v47, s[4:5]
	v_sqrt_f32_e32 v47, v44
	s_nop 0
	v_add_u32_e32 v49, -1, v47
	v_fma_f32 v50, -v49, v47, v44
	v_cmp_ge_f32_e64 s[6:7], 0, v50
	v_add_u32_e32 v50, 1, v47
	s_nop 0
	v_cndmask_b32_e64 v49, v47, v49, s[6:7]
	v_fma_f32 v47, -v50, v47, v44
	v_cmp_lt_f32_e64 s[6:7], 0, v47
	s_nop 1
	v_cndmask_b32_e64 v47, v49, v50, s[6:7]
	v_mul_f32_e32 v49, 0x37800000, v47
	v_cndmask_b32_e64 v47, v47, v49, s[4:5]
	v_cmp_class_f32_e64 s[4:5], v44, v205
	s_nop 1
	v_cndmask_b32_e64 v47, v47, v44, s[4:5]
	v_mul_f32_e32 v45, v45, v47
	v_add_u32_e32 v44, 0x1c00, v74
	v_mul_f32_e32 v45, v73, v45
	ds_write2_b32 v44, v68, v46 offset0:38 offset1:54
	ds_write2_b32 v66, v70, v45 offset0:6 offset1:22
	v_mov_b32_e32 v40, v162
	v_mov_b32_e32 v41, v163
	v_mov_b32_e32 v42, v164
	s_waitcnt vmcnt(2)
	v_add_f32_e32 v32, v32, v40
	v_mul_f32_e32 v32, 0xbfb8aa3b, v32
	v_exp_f32_e32 v32, v32
	s_waitcnt vmcnt(1)
	v_add_f32_e32 v28, v28, v41
	v_mul_f32_e32 v28, 0xbfb8aa3b, v28
	v_exp_f32_e32 v28, v28
	v_add_f32_e32 v32, 1.0, v32
	v_rcp_f32_e32 v32, v32
	v_add_f32_e32 v29, v29, v41
	v_add_f32_e32 v28, 1.0, v28
	v_rcp_f32_e32 v28, v28
	v_mul_f32_e32 v32, 0xc1000000, v32
	s_waitcnt vmcnt(0)
; __device__ __forceinline__ float fexp(float x) { return __builtin_amdgcn_exp2f(x * LOG2E); }
; __device__ __forceinline__ float sigm(float x) { return frcp(1.f + fexp(-x)); }
; __device__ __forceinline__ f32x4 mfma16(bf16x8 a, bf16x8 b, f32x4 c) { return __builtin_amdgcn_mfma_f32_16x16x32_bf16(a, b, c, 0, 0, 0); }
; __device__ __forceinline__ void lru_item(const Params& p, int l, int item, LAS unsigned char* lds) {
;     ...
;       for (int jt = 0; jt < 4; ++jt) {
;           f32x4 pa = mfma16(a0, wa0[jt], ZERO4); pa = mfma16(a1, wa1[jt], pa);
;           f32x4 px = mfma16(a0, wx0[jt], ZERO4); px = mfma16(a1, wx1[jt], px);
;           const int cj = l * 256 + h * 64 + jt * 16 + fr; const float bav = p.ba[cj], bxv = p.bx[cj], sp = p.spl[cj];
; #pragma unroll
;           for (int jj = 0; jj < 4; ++jj) { const int t = fq * 4 + jj; const float r = sigm(pa[jj] + bav), ig = sigm(px[jj] + bxv); const float la = -8.f * r * sp;
;               const float a = fexp(la); float mult = sqrtf(fmaxf(1.f - fexp(2.f * la), 0.f)); if (t0 + t == 0) mult = 1.f;
;               const int li = t * 66 + jt * 16 + fr; const float xcv = xf[li]; sa[li] = a; xf[li] = mult * ig * xcv; }
	v_mul_f32_e32 v32, v42, v32
	v_mul_f32_e32 v36, 0x3fb8aa3b, v32
	v_add_f32_e32 v32, v32, v32
	v_mul_f32_e32 v32, 0x3fb8aa3b, v32
	v_exp_f32_e32 v32, v32
	v_exp_f32_e32 v36, v36
	v_mul_f32_e32 v29, 0xbfb8aa3b, v29
	v_exp_f32_e32 v29, v29
	v_sub_f32_e32 v32, 1.0, v32
	v_max_f32_e32 v32, 0, v32
	v_cmp_gt_f32_e64 s[4:5], s16, v32
	v_mul_f32_e32 v37, 0x4f800000, v32
	ds_write_b32 v74, v36 offset:6656
	v_cndmask_b32_e64 v32, v32, v37, s[4:5]
	v_sqrt_f32_e32 v37, v32
	v_add_f32_e32 v29, 1.0, v29
	v_rcp_f32_e32 v29, v29
	v_add_u32_e32 v38, -1, v37
	v_fma_f32 v39, -v38, v37, v32
	v_cmp_ge_f32_e64 s[6:7], 0, v39
	v_add_u32_e32 v39, 1, v37
	s_nop 0
	v_cndmask_b32_e64 v38, v37, v38, s[6:7]
	v_fma_f32 v37, -v39, v37, v32
	v_cmp_lt_f32_e64 s[6:7], 0, v37
	s_nop 1
	v_cndmask_b32_e64 v37, v38, v39, s[6:7]
	v_mul_f32_e32 v38, 0x37800000, v37
	v_cndmask_b32_e64 v37, v37, v38, s[4:5]
	ds_read2_b32 v[38:39], v75 offset0:96 offset1:112
	v_cmp_class_f32_e64 s[4:5], v32, v205
	s_nop 1
	v_cndmask_b32_e64 v32, v37, v32, s[4:5]
	v_cndmask_b32_e64 v32, v32, 1.0, vcc
	v_mul_f32_e32 v28, v28, v32
	s_waitcnt lgkmcnt(0)
	v_mul_f32_e32 v28, v38, v28
	ds_write2_b32 v75, v48, v28 offset0:80 offset1:96
	v_add_f32_e32 v28, v33, v40
	v_mul_f32_e32 v28, 0xbfb8aa3b, v28
	v_exp_f32_e32 v28, v28
	s_nop 0
	v_add_f32_e32 v28, 1.0, v28
	v_rcp_f32_e32 v28, v28
	s_nop 0
	v_mul_f32_e32 v28, 0xc1000000, v28
	v_mul_f32_e32 v28, v42, v28
	v_mul_f32_e32 v32, 0x3fb8aa3b, v28
	v_add_f32_e32 v28, v28, v28
	v_mul_f32_e32 v28, 0x3fb8aa3b, v28
	v_exp_f32_e32 v28, v28
	v_exp_f32_e32 v32, v32
	v_sub_f32_e32 v28, 1.0, v28
	v_max_f32_e32 v28, 0, v28
	v_cmp_gt_f32_e64 s[4:5], s16, v28
	v_mul_f32_e32 v33, 0x4f800000, v28
	s_nop 0
	v_cndmask_b32_e64 v28, v28, v33, s[4:5]
	v_sqrt_f32_e32 v33, v28
	s_nop 0
	v_add_u32_e32 v36, -1, v33
	v_fma_f32 v37, -v36, v33, v28
	v_cmp_ge_f32_e64 s[6:7], 0, v37
	v_add_u32_e32 v37, 1, v33
	s_nop 0
	v_cndmask_b32_e64 v36, v33, v36, s[6:7]
	v_fma_f32 v33, -v37, v33, v28
	v_cmp_lt_f32_e64 s[6:7], 0, v33
	s_nop 1
	v_cndmask_b32_e64 v33, v36, v37, s[6:7]
	v_mul_f32_e32 v36, 0x37800000, v33
	v_cndmask_b32_e64 v33, v33, v36, s[4:5]
	ds_read2_b32 v[36:37], v75 offset0:162 offset1:178
	v_cmp_class_f32_e64 s[4:5], v28, v205
	ds_write_b32 v74, v32 offset:6920
	s_nop 0
	v_cndmask_b32_e64 v28, v33, v28, s[4:5]
	v_mul_f32_e32 v28, v29, v28
	s_waitcnt lgkmcnt(1)
	v_mul_f32_e32 v28, v36, v28
	ds_write_b32 v74, v28 offset:2696
	v_add_f32_e32 v28, v34, v40
	v_mul_f32_e32 v28, 0xbfb8aa3b, v28
	v_exp_f32_e32 v28, v28
	v_add_f32_e32 v29, v30, v41
	v_mul_f32_e32 v29, 0xbfb8aa3b, v29
	v_exp_f32_e32 v29, v29
	v_add_f32_e32 v28, 1.0, v28
	v_rcp_f32_e32 v28, v28
	v_add_f32_e32 v29, 1.0, v29
	v_rcp_f32_e32 v29, v29
	v_mul_f32_e32 v28, 0xc1000000, v28
	v_mul_f32_e32 v28, v42, v28
	v_mul_f32_e32 v30, 0x3fb8aa3b, v28
	v_add_f32_e32 v28, v28, v28
	v_mul_f32_e32 v28, 0x3fb8aa3b, v28
	v_exp_f32_e32 v28, v28
	v_exp_f32_e32 v30, v30
	v_sub_f32_e32 v28, 1.0, v28
	v_max_f32_e32 v28, 0, v28
	v_cmp_gt_f32_e64 s[4:5], s16, v28
	v_mul_f32_e32 v32, 0x4f800000, v28
	s_nop 0
	v_cndmask_b32_e64 v28, v28, v32, s[4:5]
	v_sqrt_f32_e32 v32, v28
	s_nop 0
	v_add_u32_e32 v33, -1, v32
	v_fma_f32 v34, -v33, v32, v28
	v_cmp_ge_f32_e64 s[6:7], 0, v34
	v_add_u32_e32 v34, 1, v32
	s_nop 0
	v_cndmask_b32_e64 v33, v32, v33, s[6:7]
	v_fma_f32 v32, -v34, v32, v28
	v_cmp_lt_f32_e64 s[6:7], 0, v32
	s_nop 1
	v_cndmask_b32_e64 v32, v33, v34, s[6:7]
	v_mul_f32_e32 v33, 0x37800000, v32
	v_cndmask_b32_e64 v32, v32, v33, s[4:5]
	v_cmp_class_f32_e64 s[4:5], v28, v205
	s_nop 1
	v_cndmask_b32_e64 v28, v32, v28, s[4:5]
	ds_read2_b32 v[32:33], v75 offset0:228 offset1:244
	v_mul_f32_e32 v28, v29, v28
	v_add_f32_e32 v29, v31, v41
	v_mul_f32_e32 v29, 0xbfb8aa3b, v29
	v_exp_f32_e32 v29, v29
	s_waitcnt lgkmcnt(0)
	v_mul_f32_e32 v28, v32, v28
	ds_write_b32 v74, v28 offset:2960
	v_add_f32_e32 v28, v35, v40
	v_mul_f32_e32 v28, 0xbfb8aa3b, v28
	v_exp_f32_e32 v28, v28
	v_add_f32_e32 v29, 1.0, v29
	v_rcp_f32_e32 v31, v29
	ds_write_b32 v74, v30 offset:7184
	v_add_f32_e32 v28, 1.0, v28
	v_rcp_f32_e32 v28, v28
	s_nop 0
	v_mul_f32_e32 v28, 0xc1000000, v28
	v_mul_f32_e32 v28, v42, v28
	v_mul_f32_e32 v29, 0x3fb8aa3b, v28
	v_add_f32_e32 v28, v28, v28
	v_mul_f32_e32 v28, 0x3fb8aa3b, v28
	v_exp_f32_e32 v28, v28
	v_exp_f32_e32 v30, v29
	v_sub_f32_e32 v28, 1.0, v28
	v_max_f32_e32 v28, 0, v28
	v_cmp_gt_f32_e64 s[4:5], s16, v28
	v_mul_f32_e32 v29, 0x4f800000, v28
	s_nop 0
	v_cndmask_b32_e64 v28, v28, v29, s[4:5]
	v_sqrt_f32_e32 v29, v28
	s_nop 0
	v_add_u32_e32 v32, -1, v29
	v_fma_f32 v34, -v32, v29, v28
	v_cmp_ge_f32_e64 s[6:7], 0, v34
	v_add_u32_e32 v34, 1, v29
	s_nop 0
	v_cndmask_b32_e64 v32, v29, v32, s[6:7]
	v_fma_f32 v29, -v34, v29, v28
	v_cmp_lt_f32_e64 s[6:7], 0, v29
	s_nop 1
	v_cndmask_b32_e64 v29, v32, v34, s[6:7]
	v_mul_f32_e32 v32, 0x37800000, v29
	v_cndmask_b32_e64 v29, v29, v32, s[4:5]
	v_cmp_class_f32_e64 s[4:5], v28, v205
	s_nop 1
	v_cndmask_b32_e64 v32, v29, v28, s[4:5]
	ds_read2_b32 v[28:29], v66 offset0:38 offset1:54
	v_mov_b32_e32 v12, v165
	v_mov_b32_e32 v13, v166
	v_mov_b32_e32 v14, v167
	v_mul_f32_e32 v31, v31, v32
	s_waitcnt lgkmcnt(0)
	v_mul_f32_e32 v28, v28, v31
	s_waitcnt vmcnt(2)
	v_add_f32_e32 v8, v8, v12
	v_mul_f32_e32 v8, 0xbfb8aa3b, v8
	v_exp_f32_e32 v8, v8
	s_waitcnt vmcnt(1)
	v_add_f32_e32 v4, v4, v13
	v_mul_f32_e32 v4, 0xbfb8aa3b, v4
	v_exp_f32_e32 v4, v4
	v_add_f32_e32 v8, 1.0, v8
	v_rcp_f32_e32 v8, v8
	v_add_f32_e32 v5, v5, v13
	v_add_f32_e32 v4, 1.0, v4
	v_rcp_f32_e32 v4, v4
	v_mul_f32_e32 v8, 0xc1000000, v8
	s_waitcnt vmcnt(0)
; __device__ __forceinline__ float fexp(float x) { return __builtin_amdgcn_exp2f(x * LOG2E); }
; __device__ __forceinline__ float sigm(float x) { return frcp(1.f + fexp(-x)); }
; __device__ __forceinline__ f32x4 mfma16(bf16x8 a, bf16x8 b, f32x4 c) { return __builtin_amdgcn_mfma_f32_16x16x32_bf16(a, b, c, 0, 0, 0); }
; __device__ __forceinline__ void lds_barrier() { asm volatile("s_waitcnt lgkmcnt(0)" ::: "memory"); __builtin_amdgcn_s_barrier(); asm volatile("" ::: "memory"); }
; __device__ __forceinline__ void lru_item(const Params& p, int l, int item, LAS unsigned char* lds) {
;     ...
;       for (int jt = 0; jt < 4; ++jt) {
;           f32x4 pa = mfma16(a0, wa0[jt], ZERO4); pa = mfma16(a1, wa1[jt], pa);
;           f32x4 px = mfma16(a0, wx0[jt], ZERO4); px = mfma16(a1, wx1[jt], px);
;           const int cj = l * 256 + h * 64 + jt * 16 + fr; const float bav = p.ba[cj], bxv = p.bx[cj], sp = p.spl[cj];
; #pragma unroll
;           for (int jj = 0; jj < 4; ++jj) { const int t = fq * 4 + jj; const float r = sigm(pa[jj] + bav), ig = sigm(px[jj] + bxv); const float la = -8.f * r * sp;
;               const float a = fexp(la); float mult = sqrtf(fmaxf(1.f - fexp(2.f * la), 0.f)); if (t0 + t == 0) mult = 1.f;
;               const int li = t * 66 + jt * 16 + fr; const float xcv = xf[li]; sa[li] = a; xf[li] = mult * ig * xcv; }
;       } }
;     lds_barrier();
	v_mul_f32_e32 v8, v14, v8
	v_mul_f32_e32 v15, 0x3fb8aa3b, v8
	v_add_f32_e32 v8, v8, v8
	v_mul_f32_e32 v8, 0x3fb8aa3b, v8
	v_exp_f32_e32 v8, v8
	v_exp_f32_e32 v15, v15
	v_mul_f32_e32 v5, 0xbfb8aa3b, v5
	v_exp_f32_e32 v5, v5
	v_sub_f32_e32 v8, 1.0, v8
	v_max_f32_e32 v8, 0, v8
	v_cmp_gt_f32_e64 s[4:5], s16, v8
	v_mul_f32_e32 v16, 0x4f800000, v8
	ds_write_b32 v74, v15 offset:6720
	v_cndmask_b32_e64 v8, v8, v16, s[4:5]
	v_sqrt_f32_e32 v16, v8
	v_add_f32_e32 v5, 1.0, v5
	v_rcp_f32_e32 v5, v5
	v_add_u32_e32 v17, -1, v16
	v_fma_f32 v18, -v17, v16, v8
	v_cmp_ge_f32_e64 s[6:7], 0, v18
	v_add_u32_e32 v18, 1, v16
	s_nop 0
	v_cndmask_b32_e64 v17, v16, v17, s[6:7]
	v_fma_f32 v16, -v18, v16, v8
	v_cmp_lt_f32_e64 s[6:7], 0, v16
	s_nop 1
	v_cndmask_b32_e64 v16, v17, v18, s[6:7]
	v_mul_f32_e32 v17, 0x37800000, v16
	v_cndmask_b32_e64 v16, v16, v17, s[4:5]
	v_cmp_class_f32_e64 s[4:5], v8, v205
	s_nop 1
	v_cndmask_b32_e64 v8, v16, v8, s[4:5]
	v_cndmask_b32_e64 v8, v8, 1.0, vcc
	v_mul_f32_e32 v4, v4, v8
	v_mul_f32_e32 v4, v39, v4
	ds_write_b32 v74, v4 offset:2496
	v_add_f32_e32 v4, v9, v12
	v_mul_f32_e32 v4, 0xbfb8aa3b, v4
	v_exp_f32_e32 v4, v4
	s_nop 0
	v_add_f32_e32 v4, 1.0, v4
	v_rcp_f32_e32 v4, v4
	s_nop 0
	v_mul_f32_e32 v4, 0xc1000000, v4
	v_mul_f32_e32 v4, v14, v4
	v_mul_f32_e32 v8, 0x3fb8aa3b, v4
	v_add_f32_e32 v4, v4, v4
	v_mul_f32_e32 v4, 0x3fb8aa3b, v4
	v_exp_f32_e32 v4, v4
	v_exp_f32_e32 v8, v8
	v_sub_f32_e32 v4, 1.0, v4
	v_max_f32_e32 v4, 0, v4
	v_cmp_gt_f32_e32 vcc, s16, v4
	v_mul_f32_e32 v9, 0x4f800000, v4
	ds_write_b32 v74, v8 offset:6984
	v_cndmask_b32_e32 v4, v4, v9, vcc
	v_sqrt_f32_e32 v9, v4
	s_nop 0
	v_add_u32_e32 v15, -1, v9
	v_fma_f32 v16, -v15, v9, v4
	v_cmp_ge_f32_e64 s[4:5], 0, v16
	v_add_u32_e32 v16, 1, v9
	s_nop 0
	v_cndmask_b32_e64 v15, v9, v15, s[4:5]
	v_fma_f32 v9, -v16, v9, v4
	v_cmp_lt_f32_e64 s[4:5], 0, v9
	s_nop 1
	v_cndmask_b32_e64 v9, v15, v16, s[4:5]
	v_mul_f32_e32 v15, 0x37800000, v9
	v_cndmask_b32_e32 v9, v9, v15, vcc
	v_cmp_class_f32_e32 vcc, v4, v205
	s_nop 1
	v_cndmask_b32_e32 v4, v9, v4, vcc
	v_mul_f32_e32 v4, v5, v4
	v_mul_f32_e32 v4, v37, v4
	ds_write_b32 v74, v4 offset:2760
	v_add_f32_e32 v4, v10, v12
	v_mul_f32_e32 v4, 0xbfb8aa3b, v4
	v_exp_f32_e32 v4, v4
	v_add_f32_e32 v5, v6, v13
	v_mul_f32_e32 v5, 0xbfb8aa3b, v5
	v_exp_f32_e32 v5, v5
	v_add_f32_e32 v4, 1.0, v4
	v_rcp_f32_e32 v4, v4
	v_add_f32_e32 v5, 1.0, v5
	v_rcp_f32_e32 v5, v5
	v_mul_f32_e32 v4, 0xc1000000, v4
	v_mul_f32_e32 v4, v14, v4
	v_mul_f32_e32 v6, 0x3fb8aa3b, v4
	v_add_f32_e32 v4, v4, v4
	v_mul_f32_e32 v4, 0x3fb8aa3b, v4
	v_exp_f32_e32 v4, v4
	v_exp_f32_e32 v6, v6
	v_sub_f32_e32 v4, 1.0, v4
	v_max_f32_e32 v4, 0, v4
	v_cmp_gt_f32_e32 vcc, s16, v4
	v_mul_f32_e32 v8, 0x4f800000, v4
	ds_write_b32 v74, v6 offset:7248
	v_cndmask_b32_e32 v4, v4, v8, vcc
	v_sqrt_f32_e32 v8, v4
	s_nop 0
	v_add_u32_e32 v9, -1, v8
	v_fma_f32 v10, -v9, v8, v4
	v_cmp_ge_f32_e64 s[4:5], 0, v10
	v_add_u32_e32 v10, 1, v8
	s_nop 0
	v_cndmask_b32_e64 v9, v8, v9, s[4:5]
	v_fma_f32 v8, -v10, v8, v4
	v_cmp_lt_f32_e64 s[4:5], 0, v8
	s_nop 1
	v_cndmask_b32_e64 v8, v9, v10, s[4:5]
	v_mul_f32_e32 v9, 0x37800000, v8
	v_cndmask_b32_e32 v8, v8, v9, vcc
	v_cmp_class_f32_e32 vcc, v4, v205
	s_nop 1
	v_cndmask_b32_e32 v4, v8, v4, vcc
	v_mul_f32_e32 v4, v5, v4
	v_mul_f32_e32 v4, v33, v4
	ds_write_b32 v74, v4 offset:3024
	v_add_f32_e32 v4, v11, v12
	v_mul_f32_e32 v4, 0xbfb8aa3b, v4
	v_exp_f32_e32 v4, v4
	v_add_f32_e32 v5, v7, v13
	v_mul_f32_e32 v5, 0xbfb8aa3b, v5
	v_exp_f32_e32 v5, v5
	v_add_f32_e32 v4, 1.0, v4
	v_rcp_f32_e32 v4, v4
	v_add_f32_e32 v5, 1.0, v5
	v_rcp_f32_e32 v5, v5
	v_mul_f32_e32 v4, 0xc1000000, v4
	v_mul_f32_e32 v4, v14, v4
	v_mul_f32_e32 v6, 0x3fb8aa3b, v4
	v_add_f32_e32 v4, v4, v4
	v_mul_f32_e32 v4, 0x3fb8aa3b, v4
	v_exp_f32_e32 v4, v4
	v_exp_f32_e32 v6, v6
	v_lshl_add_u32 v14, v3, 2, v79
	v_sub_f32_e32 v4, 1.0, v4
	v_max_f32_e32 v4, 0, v4
	v_cmp_gt_f32_e32 vcc, s16, v4
	v_mul_f32_e32 v7, 0x4f800000, v4
	ds_write2_b32 v44, v30, v6 offset0:70 offset1:86
	v_cndmask_b32_e32 v4, v4, v7, vcc
	v_sqrt_f32_e32 v7, v4
	s_nop 0
	v_add_u32_e32 v8, -1, v7
	v_fma_f32 v9, -v8, v7, v4
	v_cmp_ge_f32_e64 s[4:5], 0, v9
	v_add_u32_e32 v9, 1, v7
	s_nop 0
	v_cndmask_b32_e64 v8, v7, v8, s[4:5]
	v_fma_f32 v7, -v9, v7, v4
	v_cmp_lt_f32_e64 s[4:5], 0, v7
	s_nop 1
	v_cndmask_b32_e64 v7, v8, v9, s[4:5]
	v_mul_f32_e32 v8, 0x37800000, v7
	v_cndmask_b32_e32 v7, v7, v8, vcc
	v_cmp_class_f32_e32 vcc, v4, v205
	s_nop 1
	v_cndmask_b32_e32 v4, v7, v4, vcc
	v_mul_f32_e32 v4, v5, v4
	v_mul_f32_e32 v4, v29, v4
	ds_write2_b32 v66, v28, v4 offset0:38 offset1:54
	s_waitcnt lgkmcnt(0)
	s_barrier
; __device__ __forceinline__ void lds_barrier() { asm volatile("s_waitcnt lgkmcnt(0)" ::: "memory"); __builtin_amdgcn_s_barrier(); asm volatile("" ::: "memory"); }
; __device__ __forceinline__ void lru_item(const Params& p, int l, int item, LAS unsigned char* lds) {
;     ...
;     float Ac[16], Hl[16];
;     { float A = 1.f, H = 0.f;
; #pragma unroll
;       for (int i = 0; i < 16; ++i) { const float a = sa[i * 66 + lane], bt = xf[i * 66 + lane]; H = a * H + bt; A *= a; Ac[i] = A; Hl[i] = H; }
;       ct[(wid * 64 + lane) * 2] = A; ct[(wid * 64 + lane) * 2 + 1] = H; }
;     lds_barrier();
;     { float Ain = 1.f, Hin = 0.f;
;       for (int w = 0; w < wid; ++w) { const float aw = ct[(w * 64 + lane) * 2], hw = ct[(w * 64 + lane) * 2 + 1]; Hin = aw * Hin + hw; Ain *= aw; }
	v_add_u32_e32 v4, 0x1800, v14
	ds_read2_b32 v[22:23], v4 offset0:30 offset1:96
	ds_read_b32 v18, v80 offset:2304
	ds_read2_b32 v[6:7], v4 offset0:162 offset1:228
	v_add_u32_e32 v4, 0x800, v14
	ds_read2_b32 v[20:21], v4 offset0:130 offset1:196
	v_add_u32_e32 v4, 0x1c00, v14
	v_add_u32_e32 v5, 0xc00, v14
	ds_read2_b32 v[8:9], v4 offset0:38 offset1:104
	ds_read2_b32 v[12:13], v5 offset0:6 offset1:72
	s_waitcnt lgkmcnt(4)
	v_fmac_f32_e32 v18, 0, v23
	ds_read2_b32 v[46:47], v4 offset0:170 offset1:236
	ds_read2_b32 v[10:11], v5 offset0:138 offset1:204
	s_waitcnt lgkmcnt(4)
	v_fma_f32 v19, v18, v6, v20
	v_fmac_f32_e32 v21, v19, v7
	s_waitcnt lgkmcnt(2)
	v_fma_f32 v25, v21, v8, v12
	v_fmac_f32_e32 v13, v25, v9
	v_mul_f32_e32 v28, v23, v6
	s_waitcnt lgkmcnt(0)
	v_fma_f32 v17, v13, v46, v10
	v_add_u32_e32 v6, 0x2000, v14
	v_add_u32_e32 v10, 0x1000, v14
	ds_read2_b32 v[40:41], v6 offset0:46 offset1:112
	ds_read2_b32 v[4:5], v10 offset0:14 offset1:80
	ds_read2_b32 v[38:39], v6 offset0:178 offset1:244
	ds_read2_b32 v[42:43], v10 offset0:146 offset1:212
	v_fmac_f32_e32 v11, v17, v47
	v_mov_b32_e32 v6, v7
	v_mov_b32_e32 v26, v8
	s_waitcnt lgkmcnt(2)
	v_fma_f32 v15, v11, v40, v4
	v_fmac_f32_e32 v5, v15, v41
	v_mov_b32_e32 v29, v5
	s_waitcnt lgkmcnt(1)
	v_mov_b32_e32 v7, v38
	v_add_u32_e32 v4, 0x2400, v14
	v_pk_mul_f32 v[32:33], v[28:29], v[6:7]
	s_waitcnt lgkmcnt(0)
	v_mov_b32_e32 v27, v42
	ds_read2_b32 v[48:49], v4 offset0:54 offset1:120
	v_pk_mul_f32 v[36:37], v[32:33], v[26:27]
	v_pk_fma_f32 v[6:7], v[28:29], v[6:7], v[26:27]
	v_mov_b32_e32 v8, v9
	v_mov_b32_e32 v37, v7
	v_mov_b32_e32 v9, v39
	v_pk_mul_f32 v[26:27], v[36:37], v[8:9]
	v_mov_b32_e32 v42, v46
	v_add_u32_e32 v6, 0x1400, v14
	v_pk_mul_f32 v[30:31], v[26:27], v[42:43]
	v_pk_fma_f32 v[8:9], v[36:37], v[8:9], v[42:43]
	ds_read2_b32 v[50:51], v6 offset0:22 offset1:88
	ds_read2_b32 v[42:43], v4 offset0:186 offset1:252
	ds_read2_b32 v[44:45], v6 offset0:154 offset1:220
	ds_read_b32 v67, v14 offset:10488
	v_mov_b32_e32 v31, v9
	v_mov_b32_e32 v46, v47
	s_waitcnt lgkmcnt(4)
	v_mov_b32_e32 v47, v48
	v_pk_mul_f32 v[60:61], v[30:31], v[46:47]
	v_mov_b32_e32 v52, v40
	s_waitcnt lgkmcnt(3)
	v_mov_b32_e32 v53, v50
	v_pk_mul_f32 v[64:65], v[60:61], v[52:53]
	v_pk_fma_f32 v[52:53], v[30:31], v[46:47], v[52:53]
	v_mov_b32_e32 v40, v41
	v_mov_b32_e32 v65, v53
	v_mov_b32_e32 v41, v49
	v_pk_mul_f32 v[54:55], v[64:65], v[40:41]
	v_mov_b32_e32 v50, v38
	v_pk_mul_f32 v[58:59], v[54:55], v[50:51]
	v_pk_fma_f32 v[40:41], v[64:65], v[40:41], v[50:51]
	v_mov_b32_e32 v38, v39
	v_mov_b32_e32 v59, v41
	s_waitcnt lgkmcnt(2)
	v_mov_b32_e32 v39, v42
	v_pk_mul_f32 v[56:57], v[58:59], v[38:39]
	v_mov_b32_e32 v46, v48
	s_waitcnt lgkmcnt(1)
	v_mov_b32_e32 v47, v44
	v_pk_mul_f32 v[62:63], v[56:57], v[46:47]
	v_pk_fma_f32 v[46:47], v[58:59], v[38:39], v[46:47]
	v_mov_b32_e32 v38, v49
	v_mov_b32_e32 v63, v47
	v_mov_b32_e32 v39, v43
	v_pk_mul_f32 v[48:49], v[62:63], v[38:39]
	v_mov_b32_e32 v44, v42
	v_pk_mul_f32 v[50:51], v[48:49], v[44:45]
	v_pk_fma_f32 v[38:39], v[62:63], v[38:39], v[44:45]
	v_mov_b32_e32 v66, v43
	v_mov_b32_e32 v51, v39
	s_waitcnt lgkmcnt(0)
	v_pk_mul_f32 v[44:45], v[50:51], v[66:67]
	v_mov_b32_e32 v68, v67
	v_mov_b32_e32 v69, v22
	v_pk_mul_f32 v[42:43], v[44:45], v[68:69]
	v_pk_fma_f32 v[66:67], v[50:51], v[66:67], v[68:69]
	v_mul_f32_e32 v34, 0, v23
	v_mov_b32_e32 v43, v67
	ds_write_b64 v1, v[42:43]
	s_waitcnt lgkmcnt(0)
	s_barrier
	v_cmp_lt_i32_e32 vcc, 0, v0
	v_mov_b32_e32 v8, 1.0
	s_and_saveexec_b64 s[4:5], vcc
	s_cbranch_execz .LBB0_397
	v_readlane_b32 s6, v255, 9
	v_mov_b32_e32 v8, 1.0
	v_mov_b32_e32 v77, 0
	v_lshl_add_u32 v1, v3, 3, s6
	s_mov_b64 s[6:7], 0
	v_mov_b32_e32 v4, v0
